# stack24 + row-norm loops (P0 x-norm, P7, P11): ds_bpermute all-reduce replaced by DPP adds + readlane; P7 gain vector preloaded, counted vmcnt waits
# baseline (speedup 1.0000x reference)
.LBB0_76:
	global_load_dwordx4 v[0:3], v[18:19], off offset:-3072
	global_load_dwordx4 v[4:7], v[18:19], off offset:-2048
	global_load_dwordx4 v[8:11], v[18:19], off
	global_load_dwordx4 v[12:15], v[18:19], off offset:-1024
	v_add_co_u32_e32 v42, vcc, 0xfffff000, v18
	s_add_i32 s17, s17, s22
	s_nop 0
	v_addc_co_u32_e32 v43, vcc, -1, v19, vcc
	global_load_dwordx4 v[30:33], v[42:43], off offset:-3072
	global_load_dwordx4 v[34:37], v[42:43], off offset:-2048
	global_load_dwordx4 v[38:41], v[42:43], off offset:-1024
	global_load_dwordx4 v[46:49], v[18:19], off offset:-4096
	s_cmpk_gt_i32 s17, 0x3fff
	v_lshl_add_u64 v[18:19], v[18:19], 0, s[6:7]
	s_waitcnt vmcnt(7)
	v_mul_f32_e32 v29, v0, v0
	s_waitcnt vmcnt(6)
	v_pk_mul_f32 v[42:43], v[6:7], v[6:7]
	v_pk_mul_f32 v[50:51], v[4:5], v[4:5]
	s_waitcnt vmcnt(4)
	v_mul_f32_e32 v52, v13, v13
	v_mul_f32_e32 v54, v15, v15
	v_mul_f32_e32 v75, v8, v8
	v_mul_f32_e32 v76, v9, v9
	v_mul_f32_e32 v69, v10, v10
	v_mov_b32_e32 v58, v8
	v_mov_b32_e32 v59, v10
	v_mov_b32_e32 v10, v9
	v_pk_mov_b32 v[8:9], v[50:51], v[42:43] op_sel:[1,0]
	v_mov_b32_e32 v51, v43
	v_pk_fma_f32 v[42:43], v[12:13], v[12:13], v[52:53] op_sel_hi:[1,1,0]
	v_pk_fma_f32 v[52:53], v[14:15], v[14:15], v[54:55] op_sel_hi:[1,1,0]
	s_waitcnt vmcnt(3)
	v_mov_b32_e32 v54, v31
	s_waitcnt vmcnt(2)
	v_mov_b32_e32 v55, v35
	v_mov_b32_e32 v62, v33
	v_mov_b32_e32 v63, v37
	v_mul_f32_e32 v45, v1, v1
	v_mul_f32_e32 v71, v2, v2
	v_mul_f32_e32 v72, v11, v11
	v_mov_b32_e32 v56, v0
	v_mov_b32_e32 v57, v2
	v_mov_b32_e32 v2, v1
	v_mov_b32_e32 v0, v4
	v_mov_b32_e32 v1, v6
	v_mov_b32_e32 v6, v5
	v_mov_b32_e32 v4, v12
	v_mov_b32_e32 v5, v14
	v_mov_b32_e32 v14, v13
	v_mov_b32_e32 v12, v30
	v_mov_b32_e32 v13, v34
	v_mov_b32_e32 v60, v32
	v_mov_b32_e32 v61, v36
	s_waitcnt vmcnt(1)
	v_pk_mul_f32 v[64:65], v[40:41], v[40:41]
	v_pk_mul_f32 v[66:67], v[38:39], v[38:39]
	s_waitcnt vmcnt(0)
	v_mul_f32_e32 v68, v47, v47
	v_mul_f32_e32 v70, v49, v49
	v_pk_mul_f32 v[54:55], v[54:55], v[54:55]
	v_pk_mul_f32 v[62:63], v[62:63], v[62:63]
	v_pk_add_f32 v[8:9], v[8:9], v[50:51]
	v_mov_b32_e32 v43, v69
	v_mov_b32_e32 v53, v72
	v_mov_b32_e32 v50, v30
	v_mov_b32_e32 v51, v32
	v_mov_b32_e32 v32, v31
	v_mov_b32_e32 v30, v34
	v_mov_b32_e32 v31, v36
	v_mov_b32_e32 v36, v35
	v_mov_b32_e32 v34, v38
	v_mov_b32_e32 v35, v40
	v_mov_b32_e32 v40, v39
	v_mov_b32_e32 v38, v46
	v_mov_b32_e32 v39, v48
	v_pk_mov_b32 v[72:73], v[66:67], v[64:65] op_sel:[1,0]
	v_mov_b32_e32 v67, v65
	v_pk_fma_f32 v[64:65], v[46:47], v[46:47], v[68:69] op_sel_hi:[1,1,0]
	v_pk_fma_f32 v[68:69], v[48:49], v[48:49], v[70:71] op_sel_hi:[1,1,0]
	v_mov_b32_e32 v48, v47
	v_pk_fma_f32 v[12:13], v[12:13], v[12:13], v[54:55]
	v_pk_fma_f32 v[46:47], v[60:61], v[60:61], v[62:63]
	v_pk_add_f32 v[42:43], v[42:43], v[52:53]
	v_pk_add_f32 v[52:53], v[72:73], v[66:67]
	v_pk_add_f32 v[12:13], v[12:13], v[46:47]
	v_mul_f32_e32 v74, v3, v3
	v_pk_add_f32 v[46:47], v[52:53], v[52:53] op_sel:[0,1] op_sel_hi:[1,0]
	v_pk_add_f32 v[12:13], v[12:13], v[12:13] op_sel:[0,1] op_sel_hi:[1,0]
	v_mov_b32_e32 v65, v71
	v_mov_b32_e32 v69, v74
	v_mov_b32_e32 v47, v45
	v_mov_b32_e32 v13, v29
	v_pk_add_f32 v[52:53], v[64:65], v[68:69]
	v_pk_add_f32 v[12:13], v[12:13], v[46:47]
	v_pk_add_f32 v[8:9], v[8:9], v[8:9] op_sel:[0,1] op_sel_hi:[1,0]
	v_pk_add_f32 v[12:13], v[12:13], v[52:53]
	v_mov_b32_e32 v9, v76
	v_pk_add_f32 v[12:13], v[12:13], v[12:13] op_sel:[0,1] op_sel_hi:[1,0]
	s_nop 0
	v_mov_b32_e32 v13, v75
	v_pk_add_f32 v[8:9], v[12:13], v[8:9]
	s_nop 0
	v_pk_add_f32 v[8:9], v[8:9], v[42:43]
	s_nop 0
	v_add_f32_e32 v8, v8, v9
	s_nop 1
	v_add_f32_dpp v8, v8, v8 quad_perm:[1,0,3,2] row_mask:0xf bank_mask:0xf
	s_nop 1
	v_add_f32_dpp v8, v8, v8 quad_perm:[2,3,0,1] row_mask:0xf bank_mask:0xf
	s_nop 1
	v_add_f32_dpp v8, v8, v8 row_half_mirror row_mask:0xf bank_mask:0xf
	s_nop 1
	v_add_f32_dpp v8, v8, v8 row_mirror row_mask:0xf bank_mask:0xf
	s_nop 1
	v_add_f32_dpp v8, v8, v8 row_bcast:15 row_mask:0xa bank_mask:0xf
	s_nop 1
	v_add_f32_dpp v8, v8, v8 row_bcast:31 row_mask:0xc bank_mask:0xf
	s_nop 0
	v_readlane_b32 s2, v8, 63
	v_mov_b32_e32 v8, s2
	v_fmamk_f32 v8, v8, 0x3a000000, v26
	v_mul_f32_e32 v9, 0x4f800000, v8
	v_cmp_gt_f32_e32 vcc, s11, v8
	s_nop 1
	v_cndmask_b32_e32 v8, v8, v9, vcc
	v_sqrt_f32_e32 v9, v8
	s_nop 0
	v_add_u32_e32 v12, -1, v9
	v_add_u32_e32 v13, 1, v9
	v_fma_f32 v29, -v12, v9, v8
	v_fma_f32 v42, -v13, v9, v8
	v_cmp_ge_f32_e64 s[2:3], 0, v29
	s_nop 1
	v_cndmask_b32_e64 v9, v9, v12, s[2:3]
	v_cmp_lt_f32_e64 s[2:3], 0, v42
	s_nop 1
	v_cndmask_b32_e64 v9, v9, v13, s[2:3]
	v_mul_f32_e32 v12, 0x37800000, v9
	v_cndmask_b32_e32 v9, v9, v12, vcc
	v_cmp_class_f32_e32 vcc, v8, v27
	s_nop 1
	v_cndmask_b32_e32 v8, v9, v8, vcc
	v_div_scale_f32 v9, s[2:3], v8, v8, 1.0
	v_rcp_f32_e32 v13, v9
	v_div_scale_f32 v12, vcc, 1.0, v8, 1.0
	v_fma_f32 v29, -v9, v13, 1.0
	v_fmac_f32_e32 v13, v29, v13
	v_mul_f32_e32 v29, v12, v13
	v_fma_f32 v42, -v9, v29, v12
	v_fmac_f32_e32 v29, v42, v13
	v_fma_f32 v9, -v9, v29, v12
	v_div_fmas_f32 v9, v9, v13, v29
	v_div_fixup_f32 v8, v9, v8, 1.0
	v_pk_mul_f32 v[12:13], v[8:9], v[50:51] op_sel_hi:[0,1]
	v_pk_mul_f32 v[32:33], v[8:9], v[32:33] op_sel_hi:[0,1]
	v_pk_mul_f32 v[30:31], v[8:9], v[30:31] op_sel_hi:[0,1]
	v_pk_mul_f32 v[36:37], v[8:9], v[36:37] op_sel_hi:[0,1]
	v_pk_mul_f32 v[34:35], v[8:9], v[34:35] op_sel_hi:[0,1]
	v_pk_mul_f32 v[40:41], v[8:9], v[40:41] op_sel_hi:[0,1]
	v_pk_mul_f32 v[38:39], v[8:9], v[38:39] op_sel_hi:[0,1]
	v_pk_mul_f32 v[42:43], v[8:9], v[48:49] op_sel_hi:[0,1]
	v_pk_mul_f32 v[46:47], v[8:9], v[56:57] op_sel_hi:[0,1]
	v_pk_mul_f32 v[2:3], v[8:9], v[2:3] op_sel_hi:[0,1]
	v_pk_mul_f32 v[0:1], v[8:9], v[0:1] op_sel_hi:[0,1]
	v_pk_mul_f32 v[6:7], v[8:9], v[6:7] op_sel_hi:[0,1]
	v_pk_mul_f32 v[4:5], v[8:9], v[4:5] op_sel_hi:[0,1]
	v_pk_mul_f32 v[14:15], v[8:9], v[14:15] op_sel_hi:[0,1]
	v_pk_mul_f32 v[48:49], v[8:9], v[58:59] op_sel_hi:[0,1]
	v_pk_mul_f32 v[8:9], v[8:9], v[10:11] op_sel_hi:[0,1]
	v_and_b32_sdwa v10, v13, v28 dst_sel:DWORD dst_unused:UNUSED_PAD src0_sel:WORD_1 src1_sel:DWORD
	v_and_b32_sdwa v11, v12, v28 dst_sel:DWORD dst_unused:UNUSED_PAD src0_sel:WORD_1 src1_sel:DWORD
	v_and_b32_sdwa v29, v33, v28 dst_sel:DWORD dst_unused:UNUSED_PAD src0_sel:WORD_1 src1_sel:DWORD
	v_and_b32_sdwa v45, v32, v28 dst_sel:DWORD dst_unused:UNUSED_PAD src0_sel:WORD_1 src1_sel:DWORD
	v_and_b32_sdwa v50, v31, v28 dst_sel:DWORD dst_unused:UNUSED_PAD src0_sel:WORD_1 src1_sel:DWORD
	v_and_b32_sdwa v51, v30, v28 dst_sel:DWORD dst_unused:UNUSED_PAD src0_sel:WORD_1 src1_sel:DWORD
	v_and_b32_sdwa v52, v37, v28 dst_sel:DWORD dst_unused:UNUSED_PAD src0_sel:WORD_1 src1_sel:DWORD
	v_and_b32_sdwa v53, v36, v28 dst_sel:DWORD dst_unused:UNUSED_PAD src0_sel:WORD_1 src1_sel:DWORD
	v_and_b32_sdwa v54, v35, v28 dst_sel:DWORD dst_unused:UNUSED_PAD src0_sel:WORD_1 src1_sel:DWORD
	v_and_b32_sdwa v55, v34, v28 dst_sel:DWORD dst_unused:UNUSED_PAD src0_sel:WORD_1 src1_sel:DWORD
	v_and_b32_sdwa v56, v41, v28 dst_sel:DWORD dst_unused:UNUSED_PAD src0_sel:WORD_1 src1_sel:DWORD
	v_and_b32_sdwa v57, v40, v28 dst_sel:DWORD dst_unused:UNUSED_PAD src0_sel:WORD_1 src1_sel:DWORD
	v_and_b32_sdwa v58, v39, v28 dst_sel:DWORD dst_unused:UNUSED_PAD src0_sel:WORD_1 src1_sel:DWORD
	v_and_b32_sdwa v59, v38, v28 dst_sel:DWORD dst_unused:UNUSED_PAD src0_sel:WORD_1 src1_sel:DWORD
	v_and_b32_sdwa v60, v43, v28 dst_sel:DWORD dst_unused:UNUSED_PAD src0_sel:WORD_1 src1_sel:DWORD
	v_and_b32_sdwa v61, v42, v28 dst_sel:DWORD dst_unused:UNUSED_PAD src0_sel:WORD_1 src1_sel:DWORD
	v_and_b32_sdwa v62, v47, v28 dst_sel:DWORD dst_unused:UNUSED_PAD src0_sel:WORD_1 src1_sel:DWORD
	v_and_b32_sdwa v63, v46, v28 dst_sel:DWORD dst_unused:UNUSED_PAD src0_sel:WORD_1 src1_sel:DWORD
	v_and_b32_sdwa v64, v3, v28 dst_sel:DWORD dst_unused:UNUSED_PAD src0_sel:WORD_1 src1_sel:DWORD
	v_and_b32_sdwa v65, v2, v28 dst_sel:DWORD dst_unused:UNUSED_PAD src0_sel:WORD_1 src1_sel:DWORD
	v_and_b32_sdwa v66, v1, v28 dst_sel:DWORD dst_unused:UNUSED_PAD src0_sel:WORD_1 src1_sel:DWORD
	v_and_b32_sdwa v67, v0, v28 dst_sel:DWORD dst_unused:UNUSED_PAD src0_sel:WORD_1 src1_sel:DWORD
	v_and_b32_sdwa v68, v7, v28 dst_sel:DWORD dst_unused:UNUSED_PAD src0_sel:WORD_1 src1_sel:DWORD
	v_and_b32_sdwa v69, v6, v28 dst_sel:DWORD dst_unused:UNUSED_PAD src0_sel:WORD_1 src1_sel:DWORD
	v_and_b32_sdwa v70, v5, v28 dst_sel:DWORD dst_unused:UNUSED_PAD src0_sel:WORD_1 src1_sel:DWORD
	v_and_b32_sdwa v71, v4, v28 dst_sel:DWORD dst_unused:UNUSED_PAD src0_sel:WORD_1 src1_sel:DWORD
	v_and_b32_sdwa v72, v15, v28 dst_sel:DWORD dst_unused:UNUSED_PAD src0_sel:WORD_1 src1_sel:DWORD
	v_and_b32_sdwa v73, v14, v28 dst_sel:DWORD dst_unused:UNUSED_PAD src0_sel:WORD_1 src1_sel:DWORD
	v_and_b32_sdwa v76, v9, v28 dst_sel:DWORD dst_unused:UNUSED_PAD src0_sel:WORD_1 src1_sel:DWORD
	v_and_b32_sdwa v77, v8, v28 dst_sel:DWORD dst_unused:UNUSED_PAD src0_sel:WORD_1 src1_sel:DWORD
	v_add3_u32 v11, v12, v11, s16
	v_add3_u32 v10, v13, v10, s16
	v_add3_u32 v12, v33, v29, s16
	v_add3_u32 v13, v32, v45, s16
	v_and_b32_sdwa v74, v49, v28 dst_sel:DWORD dst_unused:UNUSED_PAD src0_sel:WORD_1 src1_sel:DWORD
	v_and_b32_sdwa v75, v48, v28 dst_sel:DWORD dst_unused:UNUSED_PAD src0_sel:WORD_1 src1_sel:DWORD
	v_add3_u32 v29, v30, v51, s16
	v_add3_u32 v30, v31, v50, s16
	v_add3_u32 v31, v37, v52, s16
	v_add3_u32 v32, v36, v53, s16
	v_add3_u32 v33, v34, v55, s16
	v_add3_u32 v34, v35, v54, s16
	v_add3_u32 v35, v41, v56, s16
	v_add3_u32 v36, v40, v57, s16
	v_add3_u32 v37, v38, v59, s16
	v_add3_u32 v38, v39, v58, s16
	v_add3_u32 v39, v43, v60, s16
	v_add3_u32 v40, v42, v61, s16
	v_add3_u32 v41, v46, v63, s16
	v_add3_u32 v42, v47, v62, s16
	v_add3_u32 v3, v3, v64, s16
	v_add3_u32 v2, v2, v65, s16
	v_add3_u32 v43, v0, v67, s16
	v_add3_u32 v45, v1, v66, s16
	v_add3_u32 v0, v7, v68, s16
	v_add3_u32 v1, v6, v69, s16
	v_add3_u32 v46, v4, v71, s16
	v_add3_u32 v47, v5, v70, s16
	v_add3_u32 v4, v15, v72, s16
	v_add3_u32 v5, v14, v73, s16
	v_add3_u32 v6, v9, v76, s16
	v_add3_u32 v7, v8, v77, s16
	v_and_b32_e32 v8, 0xffff0000, v12
	v_and_b32_e32 v9, 0xffff0000, v13
	v_add3_u32 v14, v48, v75, s16
	v_add3_u32 v15, v49, v74, s16
	v_and_b32_e32 v12, 0xffff0000, v31
	v_and_b32_e32 v13, 0xffff0000, v32
	v_and_b32_e32 v31, 0xffff0000, v35
	v_and_b32_e32 v32, 0xffff0000, v36
	v_and_b32_e32 v35, 0xffff0000, v39
	v_and_b32_e32 v36, 0xffff0000, v40
	v_and_b32_e32 v39, 0xffff0000, v3
	v_and_b32_e32 v40, 0xffff0000, v2
	v_and_b32_e32 v48, 0xffff0000, v0
	v_and_b32_e32 v49, 0xffff0000, v1
	v_and_b32_e32 v50, 0xffff0000, v4
	v_and_b32_e32 v51, 0xffff0000, v5
	v_and_b32_e32 v52, 0xffff0000, v6
	v_and_b32_e32 v53, 0xffff0000, v7
	v_or_b32_sdwa v1, v8, v10 dst_sel:DWORD dst_unused:UNUSED_PAD src0_sel:DWORD src1_sel:WORD_1
	v_or_b32_sdwa v0, v9, v11 dst_sel:DWORD dst_unused:UNUSED_PAD src0_sel:DWORD src1_sel:WORD_1
	v_or_b32_sdwa v3, v12, v30 dst_sel:DWORD dst_unused:UNUSED_PAD src0_sel:DWORD src1_sel:WORD_1
	v_or_b32_sdwa v2, v13, v29 dst_sel:DWORD dst_unused:UNUSED_PAD src0_sel:DWORD src1_sel:WORD_1
	v_or_b32_sdwa v5, v31, v34 dst_sel:DWORD dst_unused:UNUSED_PAD src0_sel:DWORD src1_sel:WORD_1
	v_or_b32_sdwa v4, v32, v33 dst_sel:DWORD dst_unused:UNUSED_PAD src0_sel:DWORD src1_sel:WORD_1
	v_or_b32_sdwa v7, v35, v38 dst_sel:DWORD dst_unused:UNUSED_PAD src0_sel:DWORD src1_sel:WORD_1
	v_or_b32_sdwa v6, v36, v37 dst_sel:DWORD dst_unused:UNUSED_PAD src0_sel:DWORD src1_sel:WORD_1
	v_or_b32_sdwa v9, v39, v42 dst_sel:DWORD dst_unused:UNUSED_PAD src0_sel:DWORD src1_sel:WORD_1
	v_or_b32_sdwa v8, v40, v41 dst_sel:DWORD dst_unused:UNUSED_PAD src0_sel:DWORD src1_sel:WORD_1
	v_or_b32_sdwa v11, v48, v45 dst_sel:DWORD dst_unused:UNUSED_PAD src0_sel:DWORD src1_sel:WORD_1
	v_or_b32_sdwa v10, v49, v43 dst_sel:DWORD dst_unused:UNUSED_PAD src0_sel:DWORD src1_sel:WORD_1
	v_or_b32_sdwa v13, v50, v47 dst_sel:DWORD dst_unused:UNUSED_PAD src0_sel:DWORD src1_sel:WORD_1
	v_or_b32_sdwa v12, v51, v46 dst_sel:DWORD dst_unused:UNUSED_PAD src0_sel:DWORD src1_sel:WORD_1
	v_or_b32_sdwa v15, v52, v15 dst_sel:DWORD dst_unused:UNUSED_PAD src0_sel:DWORD src1_sel:WORD_1
	v_or_b32_sdwa v14, v53, v14 dst_sel:DWORD dst_unused:UNUSED_PAD src0_sel:DWORD src1_sel:WORD_1
	global_store_dwordx2 v[16:17], v[0:1], off offset:-3584
	global_store_dwordx2 v[16:17], v[2:3], off offset:-3072
	global_store_dwordx2 v[16:17], v[4:5], off offset:-2560
	global_store_dwordx2 v[16:17], v[6:7], off offset:-2048
	global_store_dwordx2 v[16:17], v[8:9], off offset:-1536
	global_store_dwordx2 v[16:17], v[10:11], off offset:-1024
	global_store_dwordx2 v[16:17], v[12:13], off offset:-512
	global_store_dwordx2 v[16:17], v[14:15], off
	v_lshl_add_u64 v[16:17], v[16:17], 0, s[4:5]
	s_cbranch_scc0 .LBB0_76

.LBB0_1035:
	s_cmp_lt_i32 s92, 8
	s_cselect_b64 s[4:5], -1, 0
	s_and_b64 s[4:5], s[4:5], s[2:3]
	s_andn2_b64 vcc, exec, s[4:5]
	s_cbranch_vccnz .LBB0_1039
	s_mov_b32 s2, 0
	s_ashr_i32 s3, s2, 31
	s_add_u32 s6, s0, s2
	s_addc_u32 s7, s1, s3
	s_waitcnt lgkmcnt(0)
	s_load_dwordx8 s[12:19], s[6:7], 0x38
	v_mbcnt_lo_u32_b32 v0, -1, 0
	v_mbcnt_hi_u32_b32 v1, -1, v0
	v_and_b32_e32 v0, 63, v1
	v_lshlrev_b32_e32 v2, 2, v0
	s_waitcnt lgkmcnt(0)
	global_load_dword v3, v2, s[12:13]
	global_load_dword v4, v2, s[14:15]
	global_load_dword v5, v2, s[12:13] offset:256
	global_load_dword v6, v2, s[14:15] offset:256
	global_load_dword v7, v2, s[16:17] offset:256
	global_load_dword v8, v2, s[18:19] offset:256
	global_load_dword v9, v2, s[16:17]
	global_load_dword v11, v2, s[18:19]
	v_and_b32_e32 v2, 64, v1
	v_xor_b32_e32 v10, 1, v1
	v_add_u32_e32 v2, 64, v2
	v_cmp_lt_i32_e32 vcc, v10, v2
	v_xor_b32_e32 v12, 2, v1
	v_xor_b32_e32 v13, 4, v1
	v_cndmask_b32_e32 v10, v1, v10, vcc
	v_lshlrev_b32_e32 v10, 2, v10
	v_cmp_lt_i32_e32 vcc, v12, v2
	v_xor_b32_e32 v14, 8, v1
	v_xor_b32_e32 v15, 16, v1
	v_xor_b32_e32 v16, 32, v1
	s_cmpk_gt_i32 s20, 0x3fff
	s_waitcnt vmcnt(0)
	v_mul_f32_e32 v5, v5, v6
	v_fmac_f32_e32 v5, v3, v4
	v_mul_f32_e32 v6, v7, v8
	ds_bpermute_b32 v3, v10, v5
	v_fmac_f32_e32 v6, v9, v11
	ds_bpermute_b32 v4, v10, v6
	v_cndmask_b32_e32 v7, v1, v12, vcc
	v_lshlrev_b32_e32 v11, 2, v7
	s_waitcnt lgkmcnt(1)
	v_add_f32_e32 v3, v5, v3
	ds_bpermute_b32 v5, v11, v3
	s_waitcnt lgkmcnt(1)
	v_add_f32_e32 v4, v6, v4
	ds_bpermute_b32 v6, v11, v4
	v_cmp_lt_i32_e32 vcc, v13, v2
	s_waitcnt lgkmcnt(1)
	v_add_f32_e32 v3, v3, v5
	v_cndmask_b32_e32 v7, v1, v13, vcc
	v_lshlrev_b32_e32 v12, 2, v7
	s_waitcnt lgkmcnt(0)
	v_add_f32_e32 v4, v4, v6
	ds_bpermute_b32 v5, v12, v3
	ds_bpermute_b32 v6, v12, v4
	v_cmp_lt_i32_e32 vcc, v14, v2
	s_waitcnt lgkmcnt(1)
	v_add_f32_e32 v3, v3, v5
	v_cndmask_b32_e32 v7, v1, v14, vcc
	v_lshlrev_b32_e32 v13, 2, v7
	s_waitcnt lgkmcnt(0)
	v_add_f32_e32 v4, v4, v6
	ds_bpermute_b32 v5, v13, v3
	ds_bpermute_b32 v6, v13, v4
	v_cmp_lt_i32_e32 vcc, v15, v2
	s_waitcnt lgkmcnt(1)
	v_add_f32_e32 v3, v3, v5
	v_cndmask_b32_e32 v7, v1, v15, vcc
	v_lshlrev_b32_e32 v14, 2, v7
	s_waitcnt lgkmcnt(0)
	v_add_f32_e32 v4, v4, v6
	ds_bpermute_b32 v5, v14, v3
	ds_bpermute_b32 v6, v14, v4
	v_cmp_lt_i32_e32 vcc, v16, v2
	s_waitcnt lgkmcnt(1)
	v_add_f32_e32 v3, v3, v5
	v_cndmask_b32_e32 v1, v1, v16, vcc
	v_lshlrev_b32_e32 v15, 2, v1
	s_waitcnt lgkmcnt(0)
	v_add_f32_e32 v1, v4, v6
	ds_bpermute_b32 v4, v15, v3
	ds_bpermute_b32 v2, v15, v1
	s_cbranch_scc1 .LBB0_1039
	s_waitcnt lgkmcnt(1)
	v_add_f32_e32 v4, v3, v4
	s_mov_b32 s6, 0x3fb8aa3b
	v_mul_f32_e32 v3, 0x3fb8aa3b, v4
	v_fma_f32 v5, v4, s6, -v3
	v_rndne_f32_e32 v6, v3
	v_fmac_f32_e32 v5, 0x32a5705f, v4
	v_sub_f32_e32 v3, v3, v6
	v_add_f32_e32 v3, v3, v5
	v_exp_f32_e32 v5, v3
	v_cvt_i32_f32_e32 v6, v6
	s_waitcnt lgkmcnt(0)
	v_add_f32_e32 v1, v1, v2
	v_mul_f32_e32 v2, 0x3fb8aa3b, v1
	v_rndne_f32_e32 v7, v2
	v_ldexp_f32 v5, v5, v6
	v_fma_f32 v6, v1, s6, -v2
	v_fmac_f32_e32 v6, 0x32a5705f, v1
	v_sub_f32_e32 v2, v2, v7
	s_mov_b32 s7, 0xc2ce8ed0
	v_add_f32_e32 v2, v2, v6
	v_cmp_ngt_f32_e32 vcc, s7, v4
	s_mov_b32 s8, 0x42b17218
	v_exp_f32_e32 v2, v2
	v_cvt_i32_f32_e32 v6, v7
	s_add_u32 s2, s0, s2
	v_cndmask_b32_e32 v5, 0, v5, vcc
	v_mov_b32_e32 v7, 0x7f800000
	v_cmp_nlt_f32_e32 vcc, s8, v4
	s_addc_u32 s3, s1, s3
	v_ldexp_f32 v2, v2, v6
	v_cndmask_b32_e32 v4, v7, v5, vcc
	v_cmp_ngt_f32_e32 vcc, s7, v1
	s_load_dwordx2 s[6:7], s[2:3], 0x58
	v_mov_b32_e32 v3, 0
	s_load_dwordx2 s[2:3], s[2:3], 0xc0
	v_cndmask_b32_e32 v2, 0, v2, vcc
	v_cmp_nlt_f32_e32 vcc, s8, v1
	s_ashr_i32 s21, s20, 31
	v_mov_b32_e32 v16, 0x358637bd
	v_cndmask_b32_e32 v1, v7, v2, vcc
	v_lshlrev_b32_e32 v2, 4, v0
	s_waitcnt lgkmcnt(0)
	v_lshl_add_u64 v[6:7], s[6:7], 0, v[2:3]
	s_lshl_b64 s[6:7], s[20:21], 12
	s_add_u32 s2, s2, s6
	v_sub_f32_e32 v1, v4, v1
	v_lshlrev_b32_e32 v2, 3, v0
	s_addc_u32 s3, s3, s7
	v_add_f32_e32 v4, 0x3e4ccccd, v1
	v_lshl_add_u64 v[0:1], s[2:3], 0, v[2:3]
	s_mov_b64 s[2:3], 0x16400600
	s_ashr_i32 s23, s22, 31
	v_mov_b32_e32 v5, v4
	v_lshl_add_u64 v[8:9], v[0:1], 0, s[2:3]
	s_lshl_b64 s[6:7], s[22:23], 12
	s_mov_b32 s8, 0xf800000
	v_mov_b32_e32 v17, 0x260
	s_mov_b32 s9, 0x3f4ccccd
	s_movk_i32 s11, 0x7fff
	s_mov_b32 s12, 0xf0001000
	v_mov_b32_e32 v18, 1
	s_mov_b32 s13, s20
	global_load_dwordx4 v[44:47], v[6:7], off
	global_load_dwordx4 v[48:51], v[6:7], off offset:1024
	global_load_dwordx4 v[52:55], v[6:7], off offset:2048
	global_load_dwordx4 v[56:59], v[6:7], off offset:3072
.LBB0_1038:
	v_add_co_u32_e32 v20, vcc, 0xf0000000, v8
	s_add_i32 s13, s13, s22
	s_nop 0
	v_addc_co_u32_e32 v21, vcc, -1, v9, vcc
	global_load_dwordx2 v[22:23], v[20:21], off offset:-1536
	global_load_dwordx2 v[24:25], v[20:21], off offset:-1024
	global_load_dwordx2 v[26:27], v[20:21], off offset:-512
	global_load_dwordx2 v[28:29], v[20:21], off
	s_cmpk_lt_i32 s13, 0x4000
	s_waitcnt vmcnt(3)
	v_lshlrev_b32_e32 v21, 16, v23
	v_lshlrev_b32_e32 v20, 16, v22
	s_waitcnt vmcnt(2)
	v_lshlrev_b32_e32 v31, 16, v25
	v_lshlrev_b32_e32 v30, 16, v24
	v_and_b32_e32 v23, 0xffff0000, v23
	v_and_b32_e32 v22, 0xffff0000, v22
	v_and_b32_e32 v25, 0xffff0000, v25
	v_and_b32_e32 v24, 0xffff0000, v24
	v_pk_fma_f32 v[22:23], v[4:5], v[24:25], v[22:23] neg_lo:[1,0,0] neg_hi:[1,0,0]
	v_pk_fma_f32 v[20:21], v[4:5], v[30:31], v[20:21] neg_lo:[1,0,0] neg_hi:[1,0,0]
	v_pk_mul_f32 v[24:25], v[22:23], v[22:23]
	v_mov_b32_e32 v0, v44
	v_mov_b32_e32 v1, v45
	v_mov_b32_e32 v2, v46
	v_mov_b32_e32 v3, v47
	v_mov_b32_e32 v34, v0
	v_pk_fma_f32 v[24:25], v[20:21], v[20:21], v[24:25]
	v_mov_b32_e32 v35, v2
	v_add_f32_e32 v19, v24, v25
	v_mov_b32_e32 v2, v1
	s_waitcnt vmcnt(1)
	v_lshlrev_b32_e32 v37, 16, v27
	s_waitcnt vmcnt(0)
	v_lshlrev_b32_e32 v39, 16, v29
	v_lshlrev_b32_e32 v38, 16, v28
	s_nop 1
	v_add_f32_dpp v19, v19, v19 quad_perm:[1,0,3,2] row_mask:0xf bank_mask:0xf
	v_and_b32_e32 v27, 0xffff0000, v27
	v_and_b32_e32 v29, 0xffff0000, v29
	v_and_b32_e32 v28, 0xffff0000, v28
	s_nop 1
	v_add_f32_dpp v19, v19, v19 quad_perm:[2,3,0,1] row_mask:0xf bank_mask:0xf
	s_nop 1
	v_add_f32_dpp v19, v19, v19 row_half_mirror row_mask:0xf bank_mask:0xf
	v_add_co_u32_e32 v24, vcc, s12, v8
	s_nop 1
	v_add_f32_dpp v19, v19, v19 row_mirror row_mask:0xf bank_mask:0xf
	v_addc_co_u32_e32 v25, vcc, -1, v9, vcc
	global_load_dwordx2 v[30:31], v[24:25], off offset:-3584
	global_load_dwordx2 v[32:33], v[24:25], off offset:-3072
	s_nop 1
	v_add_f32_dpp v0, v19, v19 row_bcast:15 row_mask:0xa bank_mask:0xf
	v_lshlrev_b32_e32 v36, 16, v26
	v_and_b32_e32 v26, 0xffff0000, v26
	s_nop 1
	v_add_f32_dpp v0, v0, v0 row_bcast:31 row_mask:0xc bank_mask:0xf
	s_nop 0
	v_readlane_b32 s2, v0, 63
	v_mov_b32_e32 v0, s2
	v_fmamk_f32 v0, v0, 0x3b800000, v16
	v_mul_f32_e32 v1, 0x4f800000, v0
	v_cmp_gt_f32_e32 vcc, s8, v0
	s_nop 1
	v_cndmask_b32_e32 v0, v0, v1, vcc
	v_sqrt_f32_e32 v1, v0
	s_nop 0
	v_add_u32_e32 v19, -1, v1
	v_add_u32_e32 v40, 1, v1
	v_fma_f32 v41, -v19, v1, v0
	v_fma_f32 v42, -v40, v1, v0
	v_cmp_ge_f32_e64 s[2:3], 0, v41
	s_nop 1
	v_cndmask_b32_e64 v1, v1, v19, s[2:3]
	v_cmp_lt_f32_e64 s[2:3], 0, v42
	s_nop 1
	v_cndmask_b32_e64 v1, v1, v40, s[2:3]
	v_mul_f32_e32 v19, 0x37800000, v1
	v_cndmask_b32_e32 v1, v1, v19, vcc
	v_cmp_class_f32_e32 vcc, v0, v17
	s_nop 1
	v_cndmask_b32_e32 v0, v1, v0, vcc
	v_div_scale_f32 v1, s[2:3], v0, v0, s9
	v_rcp_f32_e32 v19, v1
	v_div_scale_f32 v40, vcc, s9, v0, s9
	v_fma_f32 v41, -v1, v19, 1.0
	v_fmac_f32_e32 v19, v41, v19
	v_mul_f32_e32 v41, v40, v19
	v_fma_f32 v42, -v1, v41, v40
	v_fmac_f32_e32 v41, v42, v19
	v_fma_f32 v1, -v1, v41, v40
	v_div_fmas_f32 v1, v1, v19, v41
	v_div_fixup_f32 v0, v1, v0, s9
	v_pk_mul_f32 v[20:21], v[20:21], v[0:1] op_sel_hi:[1,0]
	v_pk_mul_f32 v[0:1], v[22:23], v[0:1] op_sel_hi:[1,0]
	v_pk_mul_f32 v[20:21], v[34:35], v[20:21]
	v_pk_mul_f32 v[0:1], v[2:3], v[0:1]
	v_and_b32_sdwa v2, v21, v18 dst_sel:DWORD dst_unused:UNUSED_PAD src0_sel:WORD_1 src1_sel:DWORD
	v_and_b32_sdwa v19, v1, v18 dst_sel:DWORD dst_unused:UNUSED_PAD src0_sel:WORD_1 src1_sel:DWORD
	v_and_b32_sdwa v22, v0, v18 dst_sel:DWORD dst_unused:UNUSED_PAD src0_sel:WORD_1 src1_sel:DWORD
	v_and_b32_sdwa v3, v20, v18 dst_sel:DWORD dst_unused:UNUSED_PAD src0_sel:WORD_1 src1_sel:DWORD
	v_add3_u32 v1, v1, v19, s11
	v_add3_u32 v0, v0, v22, s11
	v_add3_u32 v3, v20, v3, s11
	v_add3_u32 v2, v21, v2, s11
	v_and_b32_e32 v1, 0xffff0000, v1
	v_and_b32_e32 v0, 0xffff0000, v0
	v_or_b32_sdwa v1, v1, v2 dst_sel:DWORD dst_unused:UNUSED_PAD src0_sel:DWORD src1_sel:WORD_1
	v_or_b32_sdwa v0, v0, v3 dst_sel:DWORD dst_unused:UNUSED_PAD src0_sel:DWORD src1_sel:WORD_1
	global_store_dwordx2 v[8:9], v[0:1], off offset:-1536
	v_pk_fma_f32 v[22:23], v[4:5], v[28:29], v[26:27] neg_lo:[1,0,0] neg_hi:[1,0,0]
	v_pk_fma_f32 v[20:21], v[4:5], v[38:39], v[36:37] neg_lo:[1,0,0] neg_hi:[1,0,0]
	v_pk_mul_f32 v[26:27], v[22:23], v[22:23]
	s_waitcnt vmcnt(1)
	v_lshlrev_b32_e32 v35, 16, v33
	v_pk_fma_f32 v[26:27], v[20:21], v[20:21], v[26:27]
	v_and_b32_e32 v33, 0xffff0000, v33
	v_add_f32_e32 v19, v26, v27
	s_nop 1
	v_add_f32_dpp v19, v19, v19 quad_perm:[1,0,3,2] row_mask:0xf bank_mask:0xf
	s_nop 1
	v_add_f32_dpp v19, v19, v19 quad_perm:[2,3,0,1] row_mask:0xf bank_mask:0xf
	s_nop 1
	v_add_f32_dpp v19, v19, v19 row_half_mirror row_mask:0xf bank_mask:0xf
	s_nop 1
	v_add_f32_dpp v19, v19, v19 row_mirror row_mask:0xf bank_mask:0xf
	s_nop 1
	v_add_f32_dpp v19, v19, v19 row_bcast:15 row_mask:0xa bank_mask:0xf
	global_load_dwordx2 v[26:27], v[24:25], off offset:-2560
	global_load_dwordx2 v[28:29], v[24:25], off offset:-2048
	v_lshlrev_b32_e32 v25, 16, v31
	v_lshlrev_b32_e32 v24, 16, v30
	v_and_b32_e32 v31, 0xffff0000, v31
	s_nop 1
	v_add_f32_dpp v19, v19, v19 row_bcast:31 row_mask:0xc bank_mask:0xf
	s_nop 0
	v_readlane_b32 s2, v19, 63
	v_mov_b32_e32 v19, s2
	v_fmamk_f32 v19, v19, 0x3b800000, v16
	v_mul_f32_e32 v34, 0x4f800000, v19
	v_cmp_gt_f32_e32 vcc, s8, v19
	v_and_b32_e32 v30, 0xffff0000, v30
	s_nop 0
	v_cndmask_b32_e32 v19, v19, v34, vcc
	v_sqrt_f32_e32 v36, v19
	v_lshlrev_b32_e32 v34, 16, v32
	v_and_b32_e32 v32, 0xffff0000, v32
	v_add_u32_e32 v37, -1, v36
	v_add_u32_e32 v38, 1, v36
	v_fma_f32 v39, -v37, v36, v19
	v_fma_f32 v40, -v38, v36, v19
	v_cmp_ge_f32_e64 s[2:3], 0, v39
	s_nop 1
	v_cndmask_b32_e64 v36, v36, v37, s[2:3]
	v_cmp_lt_f32_e64 s[2:3], 0, v40
	s_nop 1
	v_cndmask_b32_e64 v36, v36, v38, s[2:3]
	v_mul_f32_e32 v37, 0x37800000, v36
	v_cndmask_b32_e32 v36, v36, v37, vcc
	v_cmp_class_f32_e32 vcc, v19, v17
	s_nop 1
	v_cndmask_b32_e32 v19, v36, v19, vcc
	v_div_scale_f32 v36, s[2:3], v19, v19, s9
	v_rcp_f32_e32 v37, v36
	v_div_scale_f32 v38, vcc, s9, v19, s9
	v_fma_f32 v39, -v36, v37, 1.0
	v_fmac_f32_e32 v37, v39, v37
	v_mul_f32_e32 v39, v38, v37
	v_fma_f32 v40, -v36, v39, v38
	v_fmac_f32_e32 v39, v40, v37
	v_fma_f32 v36, -v36, v39, v38
	v_div_fmas_f32 v36, v36, v37, v39
	v_div_fixup_f32 v36, v36, v19, s9
	v_pk_mul_f32 v[20:21], v[20:21], v[36:37] op_sel_hi:[1,0]
	v_pk_mul_f32 v[22:23], v[22:23], v[36:37] op_sel_hi:[1,0]
	v_mov_b32_e32 v0, v48
	v_mov_b32_e32 v1, v49
	v_mov_b32_e32 v2, v50
	v_mov_b32_e32 v3, v51
	v_mov_b32_e32 v37, v2
	v_mov_b32_e32 v2, v1
	v_mov_b32_e32 v36, v0
	v_pk_mul_f32 v[2:3], v[2:3], v[22:23]
	v_pk_mul_f32 v[0:1], v[36:37], v[20:21]
	v_and_b32_sdwa v21, v3, v18 dst_sel:DWORD dst_unused:UNUSED_PAD src0_sel:WORD_1 src1_sel:DWORD
	v_and_b32_sdwa v22, v2, v18 dst_sel:DWORD dst_unused:UNUSED_PAD src0_sel:WORD_1 src1_sel:DWORD
	v_and_b32_sdwa v19, v1, v18 dst_sel:DWORD dst_unused:UNUSED_PAD src0_sel:WORD_1 src1_sel:DWORD
	v_and_b32_sdwa v20, v0, v18 dst_sel:DWORD dst_unused:UNUSED_PAD src0_sel:WORD_1 src1_sel:DWORD
	v_add3_u32 v3, v3, v21, s11
	v_add3_u32 v2, v2, v22, s11
	v_add3_u32 v0, v0, v20, s11
	v_add3_u32 v1, v1, v19, s11
	v_and_b32_e32 v3, 0xffff0000, v3
	v_and_b32_e32 v2, 0xffff0000, v2
	v_or_b32_sdwa v1, v3, v1 dst_sel:DWORD dst_unused:UNUSED_PAD src0_sel:DWORD src1_sel:WORD_1
	v_or_b32_sdwa v0, v2, v0 dst_sel:DWORD dst_unused:UNUSED_PAD src0_sel:DWORD src1_sel:WORD_1
	global_store_dwordx2 v[8:9], v[0:1], off offset:-1024
	v_pk_fma_f32 v[22:23], v[4:5], v[32:33], v[30:31] neg_lo:[1,0,0] neg_hi:[1,0,0]
	v_pk_fma_f32 v[20:21], v[4:5], v[34:35], v[24:25] neg_lo:[1,0,0] neg_hi:[1,0,0]
	v_pk_mul_f32 v[24:25], v[22:23], v[22:23]
	s_waitcnt vmcnt(1)
	v_lshlrev_b32_e32 v31, 16, v29
	v_pk_fma_f32 v[24:25], v[20:21], v[20:21], v[24:25]
	v_and_b32_e32 v29, 0xffff0000, v29
	v_add_f32_e32 v19, v24, v25
	v_lshlrev_b32_e32 v25, 16, v27
	v_and_b32_e32 v27, 0xffff0000, v27
	s_nop 1
	v_add_f32_dpp v19, v19, v19 quad_perm:[1,0,3,2] row_mask:0xf bank_mask:0xf
	s_nop 1
	v_add_f32_dpp v19, v19, v19 quad_perm:[2,3,0,1] row_mask:0xf bank_mask:0xf
	s_nop 1
	v_add_f32_dpp v19, v19, v19 row_half_mirror row_mask:0xf bank_mask:0xf
	s_nop 1
	v_add_f32_dpp v19, v19, v19 row_mirror row_mask:0xf bank_mask:0xf
	s_nop 1
	v_add_f32_dpp v19, v19, v19 row_bcast:15 row_mask:0xa bank_mask:0xf
	v_lshlrev_b32_e32 v24, 16, v26
	v_and_b32_e32 v26, 0xffff0000, v26
	s_nop 1
	v_add_f32_dpp v19, v19, v19 row_bcast:31 row_mask:0xc bank_mask:0xf
	s_nop 0
	v_readlane_b32 s2, v19, 63
	v_mov_b32_e32 v19, s2
	v_fmamk_f32 v19, v19, 0x3b800000, v16
	v_mul_f32_e32 v30, 0x4f800000, v19
	v_cmp_gt_f32_e32 vcc, s8, v19
	s_nop 1
	v_cndmask_b32_e32 v19, v19, v30, vcc
	v_sqrt_f32_e32 v32, v19
	v_lshlrev_b32_e32 v30, 16, v28
	v_and_b32_e32 v28, 0xffff0000, v28
	v_add_u32_e32 v33, -1, v32
	v_add_u32_e32 v34, 1, v32
	v_fma_f32 v35, -v33, v32, v19
	v_fma_f32 v36, -v34, v32, v19
	v_cmp_ge_f32_e64 s[2:3], 0, v35
	s_nop 1
	v_cndmask_b32_e64 v32, v32, v33, s[2:3]
	v_cmp_lt_f32_e64 s[2:3], 0, v36
	s_nop 1
	v_cndmask_b32_e64 v32, v32, v34, s[2:3]
	v_mul_f32_e32 v33, 0x37800000, v32
	v_cndmask_b32_e32 v32, v32, v33, vcc
	v_cmp_class_f32_e32 vcc, v19, v17
	s_nop 1
	v_cndmask_b32_e32 v19, v32, v19, vcc
	v_div_scale_f32 v32, s[2:3], v19, v19, s9
	v_rcp_f32_e32 v33, v32
	v_div_scale_f32 v34, vcc, s9, v19, s9
	v_fma_f32 v35, -v32, v33, 1.0
	v_fmac_f32_e32 v33, v35, v33
	v_mul_f32_e32 v35, v34, v33
	v_fma_f32 v36, -v32, v35, v34
	v_fmac_f32_e32 v35, v36, v33
	v_fma_f32 v32, -v32, v35, v34
	v_div_fmas_f32 v32, v32, v33, v35
	v_div_fixup_f32 v32, v32, v19, s9
	v_pk_mul_f32 v[20:21], v[20:21], v[32:33] op_sel_hi:[1,0]
	v_pk_mul_f32 v[22:23], v[22:23], v[32:33] op_sel_hi:[1,0]
	v_mov_b32_e32 v0, v52
	v_mov_b32_e32 v1, v53
	v_mov_b32_e32 v2, v54
	v_mov_b32_e32 v3, v55
	v_mov_b32_e32 v33, v2
	v_mov_b32_e32 v2, v1
	v_mov_b32_e32 v32, v0
	v_pk_mul_f32 v[2:3], v[2:3], v[22:23]
	v_pk_mul_f32 v[0:1], v[32:33], v[20:21]
	v_and_b32_sdwa v21, v3, v18 dst_sel:DWORD dst_unused:UNUSED_PAD src0_sel:WORD_1 src1_sel:DWORD
	v_and_b32_sdwa v22, v2, v18 dst_sel:DWORD dst_unused:UNUSED_PAD src0_sel:WORD_1 src1_sel:DWORD
	v_and_b32_sdwa v19, v1, v18 dst_sel:DWORD dst_unused:UNUSED_PAD src0_sel:WORD_1 src1_sel:DWORD
	v_and_b32_sdwa v20, v0, v18 dst_sel:DWORD dst_unused:UNUSED_PAD src0_sel:WORD_1 src1_sel:DWORD
	v_add3_u32 v3, v3, v21, s11
	v_add3_u32 v2, v2, v22, s11
	v_add3_u32 v0, v0, v20, s11
	v_add3_u32 v1, v1, v19, s11
	v_and_b32_e32 v3, 0xffff0000, v3
	v_and_b32_e32 v2, 0xffff0000, v2
	v_or_b32_sdwa v1, v3, v1 dst_sel:DWORD dst_unused:UNUSED_PAD src0_sel:DWORD src1_sel:WORD_1
	v_or_b32_sdwa v0, v2, v0 dst_sel:DWORD dst_unused:UNUSED_PAD src0_sel:DWORD src1_sel:WORD_1
	global_store_dwordx2 v[8:9], v[0:1], off offset:-512
	v_pk_fma_f32 v[22:23], v[4:5], v[28:29], v[26:27] neg_lo:[1,0,0] neg_hi:[1,0,0]
	v_pk_fma_f32 v[20:21], v[4:5], v[30:31], v[24:25] neg_lo:[1,0,0] neg_hi:[1,0,0]
	v_pk_mul_f32 v[24:25], v[22:23], v[22:23]
	s_nop 0
	v_pk_fma_f32 v[24:25], v[20:21], v[20:21], v[24:25]
	s_nop 0
	v_add_f32_e32 v19, v24, v25
	s_nop 1
	v_add_f32_dpp v19, v19, v19 quad_perm:[1,0,3,2] row_mask:0xf bank_mask:0xf
	s_nop 1
	v_add_f32_dpp v19, v19, v19 quad_perm:[2,3,0,1] row_mask:0xf bank_mask:0xf
	s_nop 1
	v_add_f32_dpp v19, v19, v19 row_half_mirror row_mask:0xf bank_mask:0xf
	s_nop 1
	v_add_f32_dpp v19, v19, v19 row_mirror row_mask:0xf bank_mask:0xf
	s_nop 1
	v_add_f32_dpp v19, v19, v19 row_bcast:15 row_mask:0xa bank_mask:0xf
	s_nop 1
	v_add_f32_dpp v19, v19, v19 row_bcast:31 row_mask:0xc bank_mask:0xf
	s_nop 0
	v_readlane_b32 s2, v19, 63
	v_mov_b32_e32 v19, s2
	v_fmamk_f32 v19, v19, 0x3b800000, v16
	v_mul_f32_e32 v24, 0x4f800000, v19
	v_cmp_gt_f32_e32 vcc, s8, v19
	s_nop 1
	v_cndmask_b32_e32 v19, v19, v24, vcc
	v_sqrt_f32_e32 v24, v19
	s_nop 0
	v_add_u32_e32 v25, -1, v24
	v_add_u32_e32 v26, 1, v24
	v_fma_f32 v27, -v25, v24, v19
	v_fma_f32 v28, -v26, v24, v19
	v_cmp_ge_f32_e64 s[2:3], 0, v27
	s_nop 1
	v_cndmask_b32_e64 v24, v24, v25, s[2:3]
	v_cmp_lt_f32_e64 s[2:3], 0, v28
	s_nop 1
	v_cndmask_b32_e64 v24, v24, v26, s[2:3]
	v_mul_f32_e32 v25, 0x37800000, v24
	v_cndmask_b32_e32 v24, v24, v25, vcc
	v_cmp_class_f32_e32 vcc, v19, v17
	s_nop 1
	v_cndmask_b32_e32 v19, v24, v19, vcc
	v_div_scale_f32 v24, s[2:3], v19, v19, s9
	v_rcp_f32_e32 v25, v24
	v_div_scale_f32 v26, vcc, s9, v19, s9
	v_fma_f32 v27, -v24, v25, 1.0
	v_fmac_f32_e32 v25, v27, v25
	v_mul_f32_e32 v27, v26, v25
	v_fma_f32 v28, -v24, v27, v26
	v_fmac_f32_e32 v27, v28, v25
	v_fma_f32 v24, -v24, v27, v26
	v_div_fmas_f32 v24, v24, v25, v27
	v_div_fixup_f32 v24, v24, v19, s9
	v_pk_mul_f32 v[20:21], v[20:21], v[24:25] op_sel_hi:[1,0]
	v_pk_mul_f32 v[22:23], v[22:23], v[24:25] op_sel_hi:[1,0]
	v_mov_b32_e32 v0, v56
	v_mov_b32_e32 v1, v57
	v_mov_b32_e32 v2, v58
	v_mov_b32_e32 v3, v59
	v_mov_b32_e32 v25, v2
	v_mov_b32_e32 v2, v1
	v_mov_b32_e32 v24, v0
	v_pk_mul_f32 v[2:3], v[2:3], v[22:23]
	v_pk_mul_f32 v[0:1], v[24:25], v[20:21]
	v_and_b32_sdwa v21, v3, v18 dst_sel:DWORD dst_unused:UNUSED_PAD src0_sel:WORD_1 src1_sel:DWORD
	v_and_b32_sdwa v22, v2, v18 dst_sel:DWORD dst_unused:UNUSED_PAD src0_sel:WORD_1 src1_sel:DWORD
	v_and_b32_sdwa v19, v1, v18 dst_sel:DWORD dst_unused:UNUSED_PAD src0_sel:WORD_1 src1_sel:DWORD
	v_and_b32_sdwa v20, v0, v18 dst_sel:DWORD dst_unused:UNUSED_PAD src0_sel:WORD_1 src1_sel:DWORD
	v_add3_u32 v3, v3, v21, s11
	v_add3_u32 v2, v2, v22, s11
	v_add3_u32 v0, v0, v20, s11
	v_add3_u32 v1, v1, v19, s11
	v_and_b32_e32 v3, 0xffff0000, v3
	v_and_b32_e32 v2, 0xffff0000, v2
	v_or_b32_sdwa v1, v3, v1 dst_sel:DWORD dst_unused:UNUSED_PAD src0_sel:DWORD src1_sel:WORD_1
	v_or_b32_sdwa v0, v2, v0 dst_sel:DWORD dst_unused:UNUSED_PAD src0_sel:DWORD src1_sel:WORD_1
	global_store_dwordx2 v[8:9], v[0:1], off
	v_lshl_add_u64 v[8:9], v[8:9], 0, s[6:7]
	s_cbranch_scc1 .LBB0_1038

.LBB0_1395:
	global_load_dwordx4 v[4:7], v[22:23], off offset:-3072
	global_load_dwordx4 v[8:11], v[22:23], off offset:-2048
	global_load_dwordx4 v[0:3], v[22:23], off
	global_load_dwordx4 v[32:35], v[22:23], off offset:-1024
	v_add_co_u32_e32 v56, vcc, 0xfffff000, v22
	s_add_i32 s20, s20, s22
	s_nop 0
	v_addc_co_u32_e32 v57, vcc, -1, v23, vcc
	global_load_dwordx4 v[36:39], v[56:57], off offset:-3072
	global_load_dwordx4 v[40:43], v[56:57], off offset:-2048
	global_load_dwordx4 v[44:47], v[56:57], off offset:-1024
	global_load_dwordx4 v[48:51], v[22:23], off offset:-4096
	s_cmpk_lt_i32 s20, 0x4000
	s_waitcnt vmcnt(0)
	v_mul_f32_e32 v81, v4, v4
	v_pk_mul_f32 v[58:59], v[10:11], v[10:11]
	v_pk_mul_f32 v[60:61], v[8:9], v[8:9]
	v_mul_f32_e32 v62, v33, v33
	v_mul_f32_e32 v64, v35, v35
	v_mul_f32_e32 v79, v2, v2
	v_mul_f32_e32 v87, v3, v3
	v_pk_mov_b32 v[66:67], v[60:61], v[58:59] op_sel:[1,0]
	v_mov_b32_e32 v61, v59
	v_pk_fma_f32 v[58:59], v[32:33], v[32:33], v[62:63] op_sel_hi:[1,1,0]
	v_pk_fma_f32 v[62:63], v[34:35], v[34:35], v[64:65] op_sel_hi:[1,1,0]
	v_mov_b32_e32 v68, v37
	v_mov_b32_e32 v69, v41
	v_mov_b32_e32 v72, v39
	v_mov_b32_e32 v73, v43
	v_mov_b32_e32 v64, v36
	v_mov_b32_e32 v65, v40
	v_mov_b32_e32 v70, v38
	v_mov_b32_e32 v71, v42
	v_pk_mul_f32 v[74:75], v[46:47], v[46:47]
	v_pk_mul_f32 v[76:77], v[44:45], v[44:45]
	v_pk_add_f32 v[60:61], v[66:67], v[60:61]
	v_mov_b32_e32 v59, v79
	v_mov_b32_e32 v63, v87
	v_pk_mul_f32 v[66:67], v[68:69], v[68:69]
	v_pk_mul_f32 v[68:69], v[72:73], v[72:73]
	v_pk_mov_b32 v[72:73], v[76:77], v[74:75] op_sel:[1,0]
	v_mov_b32_e32 v77, v75
	v_pk_add_f32 v[58:59], v[58:59], v[62:63]
	v_pk_fma_f32 v[62:63], v[64:65], v[64:65], v[66:67]
	v_pk_fma_f32 v[64:65], v[70:71], v[70:71], v[68:69]
	v_mul_f32_e32 v78, v49, v49
	v_mul_f32_e32 v80, v51, v51
	v_pk_add_f32 v[66:67], v[72:73], v[76:77]
	v_pk_add_f32 v[62:63], v[62:63], v[64:65]
	v_mul_f32_e32 v82, v5, v5
	v_mul_f32_e32 v83, v6, v6
	v_mul_f32_e32 v84, v7, v7
	v_pk_fma_f32 v[74:75], v[48:49], v[48:49], v[78:79] op_sel_hi:[1,1,0]
	v_pk_fma_f32 v[78:79], v[50:51], v[50:51], v[80:81] op_sel_hi:[1,1,0]
	v_pk_add_f32 v[64:65], v[66:67], v[66:67] op_sel:[0,1] op_sel_hi:[1,0]
	v_pk_add_f32 v[62:63], v[62:63], v[62:63] op_sel:[0,1] op_sel_hi:[1,0]
	v_mov_b32_e32 v75, v83
	v_mov_b32_e32 v79, v84
	v_mov_b32_e32 v65, v82
	v_mov_b32_e32 v63, v81
	v_pk_add_f32 v[66:67], v[74:75], v[78:79]
	v_pk_add_f32 v[62:63], v[62:63], v[64:65]
	v_mul_f32_e32 v85, v0, v0
	v_pk_add_f32 v[62:63], v[62:63], v[66:67]
	v_mul_f32_e32 v86, v1, v1
	v_pk_add_f32 v[60:61], v[60:61], v[60:61] op_sel:[0,1] op_sel_hi:[1,0]
	v_pk_add_f32 v[62:63], v[62:63], v[62:63] op_sel:[0,1] op_sel_hi:[1,0]
	v_mov_b32_e32 v61, v86
	v_mov_b32_e32 v63, v85
	v_pk_add_f32 v[60:61], v[62:63], v[60:61]
	s_nop 0
	v_pk_add_f32 v[58:59], v[60:61], v[58:59]
	s_nop 0
	v_add_f32_e32 v58, v58, v59
	s_nop 1
	v_add_f32_dpp v58, v58, v58 quad_perm:[1,0,3,2] row_mask:0xf bank_mask:0xf
	s_nop 1
	v_add_f32_dpp v58, v58, v58 quad_perm:[2,3,0,1] row_mask:0xf bank_mask:0xf
	s_nop 1
	v_add_f32_dpp v58, v58, v58 row_half_mirror row_mask:0xf bank_mask:0xf
	s_nop 1
	v_add_f32_dpp v58, v58, v58 row_mirror row_mask:0xf bank_mask:0xf
	s_nop 1
	v_add_f32_dpp v58, v58, v58 row_bcast:15 row_mask:0xa bank_mask:0xf
	s_nop 1
	v_add_f32_dpp v58, v58, v58 row_bcast:31 row_mask:0xc bank_mask:0xf
	s_nop 0
	v_readlane_b32 s0, v58, 63
	v_mov_b32_e32 v58, s0
	v_fmamk_f32 v58, v58, 0x3a000000, v30
	v_mul_f32_e32 v59, 0x4f800000, v58
	v_cmp_gt_f32_e32 vcc, s4, v58
	s_nop 1
	v_cndmask_b32_e32 v58, v58, v59, vcc
	v_sqrt_f32_e32 v59, v58
	s_nop 0
	v_add_u32_e32 v60, -1, v59
	v_add_u32_e32 v61, 1, v59
	v_fma_f32 v62, -v60, v59, v58
	v_fma_f32 v63, -v61, v59, v58
	v_cmp_ge_f32_e64 s[0:1], 0, v62
	s_nop 1
	v_cndmask_b32_e64 v59, v59, v60, s[0:1]
	v_cmp_lt_f32_e64 s[0:1], 0, v63
	s_nop 1
	v_cndmask_b32_e64 v59, v59, v61, s[0:1]
	v_mul_f32_e32 v60, 0x37800000, v59
	v_cndmask_b32_e32 v59, v59, v60, vcc
	v_cmp_class_f32_e32 vcc, v58, v31
	s_nop 1
	v_cndmask_b32_e32 v58, v59, v58, vcc
	v_div_scale_f32 v59, s[0:1], v58, v58, 1.0
	v_rcp_f32_e32 v60, v59
	v_div_scale_f32 v61, vcc, 1.0, v58, 1.0
	v_fma_f32 v62, -v59, v60, 1.0
	v_fmac_f32_e32 v60, v62, v60
	v_mul_f32_e32 v62, v61, v60
	v_fma_f32 v63, -v59, v62, v61
	v_fmac_f32_e32 v62, v63, v60
	v_fma_f32 v59, -v59, v62, v61
	v_div_fmas_f32 v59, v59, v60, v62
	v_div_fixup_f32 v58, v59, v58, 1.0
	v_pk_mul_f32 v[36:37], v[58:59], v[36:37] op_sel_hi:[0,1]
	v_pk_mul_f32 v[38:39], v[58:59], v[38:39] op_sel_hi:[0,1]
	v_pk_mul_f32 v[38:39], v[38:39], v[90:91]
	v_pk_mul_f32 v[36:37], v[36:37], v[88:89]
	global_store_dwordx4 v[56:57], v[36:39], off offset:-3072
	v_pk_mul_f32 v[42:43], v[58:59], v[42:43] op_sel_hi:[0,1]
	v_pk_mul_f32 v[40:41], v[58:59], v[40:41] op_sel_hi:[0,1]
	v_pk_mul_f32 v[6:7], v[58:59], v[6:7] op_sel_hi:[0,1]
	v_pk_mul_f32 v[4:5], v[58:59], v[4:5] op_sel_hi:[0,1]
	v_pk_mul_f32 v[10:11], v[58:59], v[10:11] op_sel_hi:[0,1]
	v_pk_mul_f32 v[8:9], v[58:59], v[8:9] op_sel_hi:[0,1]
	v_pk_mul_f32 v[2:3], v[58:59], v[2:3] op_sel_hi:[0,1]
	v_pk_mul_f32 v[0:1], v[58:59], v[0:1] op_sel_hi:[0,1]
	v_pk_mul_f32 v[52:53], v[40:41], v[92:93]
	v_pk_mul_f32 v[54:55], v[42:43], v[94:95]
	global_store_dwordx4 v[56:57], v[52:55], off offset:-2048
	v_pk_mul_f32 v[40:41], v[58:59], v[46:47] op_sel_hi:[0,1]
	v_pk_mul_f32 v[42:43], v[58:59], v[44:45] op_sel_hi:[0,1]
	v_pk_mul_f32 v[36:37], v[42:43], v[96:97]
	v_pk_mul_f32 v[38:39], v[40:41], v[98:99]
	global_store_dwordx4 v[56:57], v[36:39], off offset:-1024
	v_pk_mul_f32 v[40:41], v[58:59], v[50:51] op_sel_hi:[0,1]
	v_pk_mul_f32 v[42:43], v[58:59], v[48:49] op_sel_hi:[0,1]
	v_pk_mul_f32 v[52:53], v[42:43], v[100:101]
	v_pk_mul_f32 v[54:55], v[40:41], v[102:103]
	global_store_dwordx4 v[22:23], v[52:55], off offset:-4096
	v_pk_mul_f32 v[4:5], v[4:5], v[104:105]
	v_pk_mul_f32 v[6:7], v[6:7], v[106:107]
	global_store_dwordx4 v[22:23], v[4:7], off offset:-3072
	v_pk_mul_f32 v[36:37], v[8:9], v[108:109]
	v_pk_mul_f32 v[38:39], v[10:11], v[110:111]
	global_store_dwordx4 v[22:23], v[36:39], off offset:-2048
	v_pk_mul_f32 v[8:9], v[58:59], v[34:35] op_sel_hi:[0,1]
	v_pk_mul_f32 v[10:11], v[58:59], v[32:33] op_sel_hi:[0,1]
	v_pk_mul_f32 v[52:53], v[10:11], v[112:113]
	v_pk_mul_f32 v[54:55], v[8:9], v[114:115]
	global_store_dwordx4 v[22:23], v[52:55], off offset:-1024
	v_pk_mul_f32 v[0:1], v[0:1], v[116:117]
	v_pk_mul_f32 v[2:3], v[2:3], v[118:119]
	global_store_dwordx4 v[22:23], v[0:3], off
	v_lshl_add_u64 v[22:23], v[22:23], 0, s[2:3]
	s_cbranch_scc1 .LBB0_1395
